# static priority: s_setprio 1 for the OLDER wave half (0-3) during attention instead of waves 4-7
# speedup vs baseline: 1.0092x; 1.0051x over previous
; __device__ __forceinline__ void attn_phase(const bf16_t* FQ, const bf16_t* FK, const bf16_t* FV, const float* cum, const float* norms, bf16_t* Y, unsigned* qctr, unsigned* flags, float* parts, lptr lds, int tid_) {
;     ...
;         int tid = tid_; asm volatile("" : "+v"(tid));
;         const int wid = __builtin_amdgcn_readfirstlane(tid >> 6), lane = tid & 63;
.LBB0_820:
	v_readfirstlane_b32 s0, v0
	s_nop 1
	s_cmp_lt_u32 s0, 0x100
	s_cbranch_scc0 .Lattn_prio_done
	s_setprio 1
